# attention unit prologue: forget-bias global->LDS copy issues its (up to 4) loads back to back under nested masks, one wait
# speedup vs baseline: 1.0193x; 1.0004x over previous
.LBB0_776:
	global_load_dwordx4 v[6:9], v[2:3], off
	s_mov_b64 s[78:79], 0x2000
	v_add_u32_e32 v0, 0x200, v0
	v_lshl_add_u64 v[2:3], v[2:3], 0, s[78:79]
	v_cmp_gt_i32_e32 vcc, s67, v0
	s_and_saveexec_b64 s[6:7], vcc
	global_load_dwordx4 v[32:35], v[2:3], off
	v_add_u32_e32 v0, 0x200, v0
	v_lshl_add_u64 v[2:3], v[2:3], 0, s[78:79]
	v_cmp_gt_i32_e32 vcc, s67, v0
	s_and_saveexec_b64 s[98:99], vcc
	global_load_dwordx4 v[36:39], v[2:3], off
	v_add_u32_e32 v0, 0x200, v0
	v_lshl_add_u64 v[2:3], v[2:3], 0, s[78:79]
	v_cmp_gt_i32_e32 vcc, s67, v0
	s_and_saveexec_b64 s[100:101], vcc
	global_load_dwordx4 v[40:43], v[2:3], off
	v_add_u32_e32 v0, 0x200, v0
	v_lshl_add_u64 v[2:3], v[2:3], 0, s[78:79]
	v_cmp_gt_i32_e32 vcc, s67, v0
	s_waitcnt vmcnt(0)
	ds_write_b128 v4, v[40:43] offset:24576
	s_mov_b64 exec, s[100:101]
	ds_write_b128 v4, v[36:39] offset:16384
	s_mov_b64 exec, s[98:99]
	ds_write_b128 v4, v[32:35] offset:8192
	s_mov_b64 exec, s[6:7]
	ds_write_b128 v4, v[6:9]
	s_mov_b64 exec, vcc
	v_add_u32_e32 v4, 0x8000, v4
	s_cbranch_execnz .LBB0_776
